# P4 hg_out gate pass 2: all 32 K/Q-word LDS reads batched into the free prefetch quads, 16 gate steps run without per-step LDS round trips
# baseline (speedup 1.0000x reference)
.LBB0_444:
	s_or_b64 exec, exec, s[14:15]
	v_mul_u32_u24_e32 v198, 0x44, v173
	v_lshl_add_u32 v198, v198, 2, v113
	ds_read_b32 v2, v198
	v_mad_u32_u24 v173, v173, s20, v102
	v_lshl_add_u32 v173, v173, 2, v135
	ds_read_b32 v3, v173
	s_ashr_i32 s14, s29, 2
	v_mul_u32_u24_e32 v199, 0x44, v172
	v_lshl_add_u32 v199, v199, 2, v113
	ds_read_b32 v4, v199
	v_mad_u32_u24 v172, v172, s20, v102
	v_lshl_add_u32 v172, v172, 2, v135
	ds_read_b32 v5, v172
	s_ashr_i32 s15, s14, 31
	global_load_dwordx4 v[50:53], v[34:35], off
	v_mul_u32_u24_e32 v200, 0x44, v171
	v_lshl_add_u32 v200, v200, 2, v113
	ds_read_b32 v6, v200
	v_mad_u32_u24 v171, v171, s20, v102
	v_lshl_add_u32 v171, v171, 2, v135
	ds_read_b32 v7, v171
	s_lshl_b64 vcc, s[14:15], 6
	v_mul_u32_u24_e32 v201, 0x44, v170
	v_lshl_add_u32 v201, v201, 2, v113
	ds_read_b32 v8, v201
	v_mad_u32_u24 v170, v170, s20, v102
	v_lshl_add_u32 v170, v170, 2, v135
	ds_read_b32 v9, v170
	s_and_b32 s14, s29, 3
	global_load_dwordx4 v[46:49], v[82:83], off offset:-192
	v_mul_u32_u24_e32 v202, 0x44, v169
	v_lshl_add_u32 v202, v202, 2, v113
	ds_read_b32 v18, v202
	v_mad_u32_u24 v169, v169, s20, v102
	v_lshl_add_u32 v169, v169, 2, v135
	ds_read_b32 v19, v169
	s_lshl_b32 s15, s14, 23
	v_mul_u32_u24_e32 v203, 0x44, v168
	v_lshl_add_u32 v203, v203, 2, v113
	ds_read_b32 v20, v203
	v_mad_u32_u24 v168, v168, s20, v102
	v_lshl_add_u32 v168, v168, 2, v135
	ds_read_b32 v21, v168
	s_add_u32 s16, s86, s15
	global_load_dwordx4 v[42:45], v[82:83], off offset:-128
	v_mul_u32_u24_e32 v204, 0x44, v95
	v_lshl_add_u32 v204, v204, 2, v113
	ds_read_b32 v22, v204
	v_mad_u32_u24 v95, v95, s20, v102
	v_lshl_add_u32 v95, v95, 2, v135
	ds_read_b32 v23, v95
	s_addc_u32 s17, s87, 0
	v_mul_u32_u24_e32 v205, 0x44, v94
	v_lshl_add_u32 v205, v205, 2, v113
	ds_read_b32 v24, v205
	v_mad_u32_u24 v94, v94, s20, v102
	v_lshl_add_u32 v94, v94, 2, v135
	ds_read_b32 v25, v94
	s_brev_b32 s15, 8
	global_load_dwordx4 v[38:41], v[82:83], off offset:-64
	v_mul_u32_u24_e32 v246, 0x44, v93
	v_lshl_add_u32 v246, v246, 2, v113
	ds_read_b32 v10, v246
	v_mad_u32_u24 v93, v93, s20, v102
	v_lshl_add_u32 v93, v93, 2, v135
	ds_read_b32 v11, v93
	s_lshl_b32 s80, s14, 9
	v_mul_u32_u24_e32 v247, 0x44, v92
	v_lshl_add_u32 v247, v247, 2, v113
	ds_read_b32 v12, v247
	v_mad_u32_u24 v92, v92, s20, v102
	v_lshl_add_u32 v92, v92, 2, v135
	ds_read_b32 v13, v92
	s_mov_b32 s29, s28
	global_load_dwordx4 v[34:37], v[82:83], off
	v_lshl_add_u64 v[82:83], v[82:83], 0, s[10:11]
	v_mul_u32_u24_e32 v248, 0x44, v91
	v_lshl_add_u32 v248, v248, 2, v113
	ds_read_b32 v14, v248
	v_mad_u32_u24 v91, v91, s20, v102
	v_lshl_add_u32 v91, v91, 2, v135
	ds_read_b32 v15, v91
	v_mul_u32_u24_e32 v249, 0x44, v90
	v_lshl_add_u32 v249, v249, 2, v113
	ds_read_b32 v16, v249
	v_mad_u32_u24 v90, v90, s20, v102
	v_lshl_add_u32 v90, v90, 2, v135
	ds_read_b32 v17, v90
	v_mul_u32_u24_e32 v250, 0x44, v89
	v_lshl_add_u32 v250, v250, 2, v113
	ds_read_b32 v26, v250
	v_mad_u32_u24 v89, v89, s20, v102
	v_lshl_add_u32 v89, v89, 2, v135
	ds_read_b32 v27, v89
	v_mul_u32_u24_e32 v251, 0x44, v88
	v_lshl_add_u32 v251, v251, 2, v113
	ds_read_b32 v28, v251
	v_mad_u32_u24 v88, v88, s20, v102
	v_lshl_add_u32 v88, v88, 2, v135
	ds_read_b32 v29, v88
	v_mul_u32_u24_e32 v252, 0x44, v87
	v_lshl_add_u32 v252, v252, 2, v113
	ds_read_b32 v30, v252
	v_mad_u32_u24 v87, v87, s20, v102
	v_lshl_add_u32 v87, v87, 2, v135
	ds_read_b32 v31, v87
	v_mul_u32_u24_e32 v253, 0x44, v86
	v_lshl_add_u32 v253, v253, 2, v113
	ds_read_b32 v32, v253
	v_mad_u32_u24 v86, v86, s20, v102
	v_lshl_add_u32 v86, v86, 2, v135
	ds_read_b32 v33, v86
	s_waitcnt lgkmcnt(15)
	v_lshlrev_b32_e32 v174, 16, v2
	v_and_b32_e32 v175, 0xffff0000, v2
	v_pk_add_f32 v[176:177], v[174:175], 1.0 op_sel_hi:[1,0] neg_lo:[1,0] neg_hi:[1,0]
	v_lshlrev_b32_e32 v244, 16, v3
	v_pk_mul_f32 v[84:85], v[84:85], v[176:177]
	v_and_b32_e32 v245, 0xffff0000, v3
	v_max_f32_e32 v176, 0xda24260, v84
	v_max_f32_e32 v177, 0xda24260, v85
	v_rcp_f32_e32 v176, v176
	v_rcp_f32_e32 v177, v177
	v_pk_mul_f32 v[244:245], v[84:85], v[244:245]
	v_pk_mul_f32 v[174:175], v[176:177], v[174:175]
	v_cvt_pk_bf16_f32 v244, v244, v245
	v_cvt_pk_bf16_f32 v174, v174, v175
	ds_write_b32 v198, v174
	ds_write_b32 v173, v244
	v_lshlrev_b32_e32 v174, 16, v4
	v_and_b32_e32 v175, 0xffff0000, v4
	v_pk_add_f32 v[176:177], v[174:175], 1.0 op_sel_hi:[1,0] neg_lo:[1,0] neg_hi:[1,0]
	v_lshlrev_b32_e32 v244, 16, v5
	v_pk_mul_f32 v[84:85], v[84:85], v[176:177]
	v_and_b32_e32 v245, 0xffff0000, v5
	v_max_f32_e32 v176, 0xda24260, v84
	v_max_f32_e32 v177, 0xda24260, v85
	v_rcp_f32_e32 v176, v176
	v_rcp_f32_e32 v177, v177
	v_pk_mul_f32 v[244:245], v[84:85], v[244:245]
	v_pk_mul_f32 v[174:175], v[176:177], v[174:175]
	v_cvt_pk_bf16_f32 v244, v244, v245
	v_cvt_pk_bf16_f32 v174, v174, v175
	ds_write_b32 v199, v174
	ds_write_b32 v172, v244
	v_lshlrev_b32_e32 v174, 16, v6
	v_and_b32_e32 v175, 0xffff0000, v6
	v_pk_add_f32 v[176:177], v[174:175], 1.0 op_sel_hi:[1,0] neg_lo:[1,0] neg_hi:[1,0]
	v_lshlrev_b32_e32 v244, 16, v7
	v_pk_mul_f32 v[84:85], v[84:85], v[176:177]
	v_and_b32_e32 v245, 0xffff0000, v7
	v_max_f32_e32 v176, 0xda24260, v84
	v_max_f32_e32 v177, 0xda24260, v85
	v_rcp_f32_e32 v176, v176
	v_rcp_f32_e32 v177, v177
	v_pk_mul_f32 v[244:245], v[84:85], v[244:245]
	v_pk_mul_f32 v[174:175], v[176:177], v[174:175]
	v_cvt_pk_bf16_f32 v244, v244, v245
	v_cvt_pk_bf16_f32 v174, v174, v175
	ds_write_b32 v200, v174
	ds_write_b32 v171, v244
	v_lshlrev_b32_e32 v174, 16, v8
	v_and_b32_e32 v175, 0xffff0000, v8
	v_pk_add_f32 v[176:177], v[174:175], 1.0 op_sel_hi:[1,0] neg_lo:[1,0] neg_hi:[1,0]
	v_lshlrev_b32_e32 v244, 16, v9
	v_pk_mul_f32 v[84:85], v[84:85], v[176:177]
	v_and_b32_e32 v245, 0xffff0000, v9
	v_max_f32_e32 v176, 0xda24260, v84
	v_max_f32_e32 v177, 0xda24260, v85
	v_rcp_f32_e32 v176, v176
	v_rcp_f32_e32 v177, v177
	v_pk_mul_f32 v[244:245], v[84:85], v[244:245]
	v_pk_mul_f32 v[174:175], v[176:177], v[174:175]
	v_cvt_pk_bf16_f32 v244, v244, v245
	v_cvt_pk_bf16_f32 v174, v174, v175
	ds_write_b32 v201, v174
	ds_write_b32 v170, v244
	v_lshlrev_b32_e32 v174, 16, v18
	v_and_b32_e32 v175, 0xffff0000, v18
	v_pk_add_f32 v[176:177], v[174:175], 1.0 op_sel_hi:[1,0] neg_lo:[1,0] neg_hi:[1,0]
	v_lshlrev_b32_e32 v244, 16, v19
	v_pk_mul_f32 v[84:85], v[84:85], v[176:177]
	v_and_b32_e32 v245, 0xffff0000, v19
	v_max_f32_e32 v176, 0xda24260, v84
	v_max_f32_e32 v177, 0xda24260, v85
	v_rcp_f32_e32 v176, v176
	v_rcp_f32_e32 v177, v177
	v_pk_mul_f32 v[244:245], v[84:85], v[244:245]
	v_pk_mul_f32 v[174:175], v[176:177], v[174:175]
	v_cvt_pk_bf16_f32 v244, v244, v245
	v_cvt_pk_bf16_f32 v174, v174, v175
	ds_write_b32 v202, v174
	ds_write_b32 v169, v244
	v_lshlrev_b32_e32 v174, 16, v20
	v_and_b32_e32 v175, 0xffff0000, v20
	v_pk_add_f32 v[176:177], v[174:175], 1.0 op_sel_hi:[1,0] neg_lo:[1,0] neg_hi:[1,0]
	v_lshlrev_b32_e32 v244, 16, v21
	v_pk_mul_f32 v[84:85], v[84:85], v[176:177]
	v_and_b32_e32 v245, 0xffff0000, v21
	v_max_f32_e32 v176, 0xda24260, v84
	v_max_f32_e32 v177, 0xda24260, v85
	v_rcp_f32_e32 v176, v176
	v_rcp_f32_e32 v177, v177
	v_pk_mul_f32 v[244:245], v[84:85], v[244:245]
	v_pk_mul_f32 v[174:175], v[176:177], v[174:175]
	v_cvt_pk_bf16_f32 v244, v244, v245
	v_cvt_pk_bf16_f32 v174, v174, v175
	ds_write_b32 v203, v174
	ds_write_b32 v168, v244
	global_load_dwordx4 v[2:5], v236, s[100:101]
	v_lshlrev_b32_e32 v174, 16, v22
	v_and_b32_e32 v175, 0xffff0000, v22
	v_pk_add_f32 v[176:177], v[174:175], 1.0 op_sel_hi:[1,0] neg_lo:[1,0] neg_hi:[1,0]
	v_lshlrev_b32_e32 v244, 16, v23
	v_pk_mul_f32 v[84:85], v[84:85], v[176:177]
	v_and_b32_e32 v245, 0xffff0000, v23
	v_max_f32_e32 v176, 0xda24260, v84
	v_max_f32_e32 v177, 0xda24260, v85
	v_rcp_f32_e32 v176, v176
	v_rcp_f32_e32 v177, v177
	v_pk_mul_f32 v[244:245], v[84:85], v[244:245]
	v_pk_mul_f32 v[174:175], v[176:177], v[174:175]
	v_cvt_pk_bf16_f32 v244, v244, v245
	v_cvt_pk_bf16_f32 v174, v174, v175
	ds_write_b32 v204, v174
	ds_write_b32 v95, v244
	v_lshlrev_b32_e32 v174, 16, v24
	v_and_b32_e32 v175, 0xffff0000, v24
	v_pk_add_f32 v[176:177], v[174:175], 1.0 op_sel_hi:[1,0] neg_lo:[1,0] neg_hi:[1,0]
	v_lshlrev_b32_e32 v244, 16, v25
	v_pk_mul_f32 v[84:85], v[84:85], v[176:177]
	v_and_b32_e32 v245, 0xffff0000, v25
	v_max_f32_e32 v176, 0xda24260, v84
	v_max_f32_e32 v177, 0xda24260, v85
	v_rcp_f32_e32 v176, v176
	v_rcp_f32_e32 v177, v177
	v_pk_mul_f32 v[244:245], v[84:85], v[244:245]
	v_pk_mul_f32 v[174:175], v[176:177], v[174:175]
	v_cvt_pk_bf16_f32 v244, v244, v245
	v_cvt_pk_bf16_f32 v174, v174, v175
	ds_write_b32 v205, v174
	ds_write_b32 v94, v244
	global_load_dwordx4 v[6:9], v237, s[100:101]
	s_waitcnt lgkmcnt(15)
	v_lshlrev_b32_e32 v174, 16, v10
	v_and_b32_e32 v175, 0xffff0000, v10
	v_pk_add_f32 v[176:177], v[174:175], 1.0 op_sel_hi:[1,0] neg_lo:[1,0] neg_hi:[1,0]
	v_lshlrev_b32_e32 v244, 16, v11
	v_pk_mul_f32 v[84:85], v[84:85], v[176:177]
	v_and_b32_e32 v245, 0xffff0000, v11
	v_max_f32_e32 v176, 0xda24260, v84
	v_max_f32_e32 v177, 0xda24260, v85
	v_rcp_f32_e32 v176, v176
	v_rcp_f32_e32 v177, v177
	v_pk_mul_f32 v[244:245], v[84:85], v[244:245]
	v_pk_mul_f32 v[174:175], v[176:177], v[174:175]
	v_cvt_pk_bf16_f32 v244, v244, v245
	v_cvt_pk_bf16_f32 v174, v174, v175
	ds_write_b32 v246, v174
	ds_write_b32 v93, v244
	v_lshlrev_b32_e32 v174, 16, v12
	v_and_b32_e32 v175, 0xffff0000, v12
	v_pk_add_f32 v[176:177], v[174:175], 1.0 op_sel_hi:[1,0] neg_lo:[1,0] neg_hi:[1,0]
	v_lshlrev_b32_e32 v244, 16, v13
	v_pk_mul_f32 v[84:85], v[84:85], v[176:177]
	v_and_b32_e32 v245, 0xffff0000, v13
	v_max_f32_e32 v176, 0xda24260, v84
	v_max_f32_e32 v177, 0xda24260, v85
	v_rcp_f32_e32 v176, v176
	v_rcp_f32_e32 v177, v177
	v_pk_mul_f32 v[244:245], v[84:85], v[244:245]
	v_pk_mul_f32 v[174:175], v[176:177], v[174:175]
	v_cvt_pk_bf16_f32 v244, v244, v245
	v_cvt_pk_bf16_f32 v174, v174, v175
	ds_write_b32 v247, v174
	ds_write_b32 v92, v244
	global_load_dwordx4 v[18:21], v238, s[100:101]
	v_lshlrev_b32_e32 v174, 16, v14
	v_and_b32_e32 v175, 0xffff0000, v14
	v_pk_add_f32 v[176:177], v[174:175], 1.0 op_sel_hi:[1,0] neg_lo:[1,0] neg_hi:[1,0]
	v_lshlrev_b32_e32 v244, 16, v15
	v_pk_mul_f32 v[84:85], v[84:85], v[176:177]
	v_and_b32_e32 v245, 0xffff0000, v15
	v_max_f32_e32 v176, 0xda24260, v84
	v_max_f32_e32 v177, 0xda24260, v85
	v_rcp_f32_e32 v176, v176
	v_rcp_f32_e32 v177, v177
	v_pk_mul_f32 v[244:245], v[84:85], v[244:245]
	v_pk_mul_f32 v[174:175], v[176:177], v[174:175]
	v_cvt_pk_bf16_f32 v244, v244, v245
	v_cvt_pk_bf16_f32 v174, v174, v175
	ds_write_b32 v248, v174
	ds_write_b32 v91, v244
	v_lshlrev_b32_e32 v174, 16, v16
	v_and_b32_e32 v175, 0xffff0000, v16
	v_pk_add_f32 v[176:177], v[174:175], 1.0 op_sel_hi:[1,0] neg_lo:[1,0] neg_hi:[1,0]
	v_lshlrev_b32_e32 v244, 16, v17
	v_pk_mul_f32 v[84:85], v[84:85], v[176:177]
	v_and_b32_e32 v245, 0xffff0000, v17
	v_max_f32_e32 v176, 0xda24260, v84
	v_max_f32_e32 v177, 0xda24260, v85
	v_rcp_f32_e32 v176, v176
	v_rcp_f32_e32 v177, v177
	v_pk_mul_f32 v[244:245], v[84:85], v[244:245]
	v_pk_mul_f32 v[174:175], v[176:177], v[174:175]
	v_cvt_pk_bf16_f32 v244, v244, v245
	v_cvt_pk_bf16_f32 v174, v174, v175
	ds_write_b32 v249, v174
	ds_write_b32 v90, v244
	global_load_dwordx4 v[22:25], v239, s[100:101]
	v_lshlrev_b32_e32 v174, 16, v26
	v_and_b32_e32 v175, 0xffff0000, v26
	v_pk_add_f32 v[176:177], v[174:175], 1.0 op_sel_hi:[1,0] neg_lo:[1,0] neg_hi:[1,0]
	v_lshlrev_b32_e32 v244, 16, v27
	v_pk_mul_f32 v[84:85], v[84:85], v[176:177]
	v_and_b32_e32 v245, 0xffff0000, v27
	v_max_f32_e32 v176, 0xda24260, v84
	v_max_f32_e32 v177, 0xda24260, v85
	v_rcp_f32_e32 v176, v176
	v_rcp_f32_e32 v177, v177
	v_pk_mul_f32 v[244:245], v[84:85], v[244:245]
	v_pk_mul_f32 v[174:175], v[176:177], v[174:175]
	v_cvt_pk_bf16_f32 v244, v244, v245
	v_cvt_pk_bf16_f32 v174, v174, v175
	ds_write_b32 v250, v174
	ds_write_b32 v89, v244
	v_lshlrev_b32_e32 v174, 16, v28
	v_and_b32_e32 v175, 0xffff0000, v28
	v_pk_add_f32 v[176:177], v[174:175], 1.0 op_sel_hi:[1,0] neg_lo:[1,0] neg_hi:[1,0]
	v_lshlrev_b32_e32 v244, 16, v29
	v_pk_mul_f32 v[84:85], v[84:85], v[176:177]
	v_and_b32_e32 v245, 0xffff0000, v29
	v_max_f32_e32 v176, 0xda24260, v84
	v_max_f32_e32 v177, 0xda24260, v85
	v_rcp_f32_e32 v176, v176
	v_rcp_f32_e32 v177, v177
	v_pk_mul_f32 v[244:245], v[84:85], v[244:245]
	v_pk_mul_f32 v[174:175], v[176:177], v[174:175]
	v_cvt_pk_bf16_f32 v244, v244, v245
	v_cvt_pk_bf16_f32 v174, v174, v175
	ds_write_b32 v251, v174
	ds_write_b32 v88, v244
	global_load_dwordx4 v[10:13], v240, s[100:101]
	v_lshlrev_b32_e32 v174, 16, v30
	v_and_b32_e32 v175, 0xffff0000, v30
	v_pk_add_f32 v[176:177], v[174:175], 1.0 op_sel_hi:[1,0] neg_lo:[1,0] neg_hi:[1,0]
	v_lshlrev_b32_e32 v244, 16, v31
	v_pk_mul_f32 v[84:85], v[84:85], v[176:177]
	v_and_b32_e32 v245, 0xffff0000, v31
	v_max_f32_e32 v176, 0xda24260, v84
	v_max_f32_e32 v177, 0xda24260, v85
	v_rcp_f32_e32 v176, v176
	v_rcp_f32_e32 v177, v177
	v_pk_mul_f32 v[244:245], v[84:85], v[244:245]
	v_pk_mul_f32 v[174:175], v[176:177], v[174:175]
	v_cvt_pk_bf16_f32 v244, v244, v245
	v_cvt_pk_bf16_f32 v174, v174, v175
	ds_write_b32 v252, v174
	ds_write_b32 v87, v244
	v_lshlrev_b32_e32 v174, 16, v32
	v_and_b32_e32 v175, 0xffff0000, v32
	v_pk_add_f32 v[176:177], v[174:175], 1.0 op_sel_hi:[1,0] neg_lo:[1,0] neg_hi:[1,0]
	v_lshlrev_b32_e32 v244, 16, v33
	v_pk_mul_f32 v[84:85], v[84:85], v[176:177]
	v_and_b32_e32 v245, 0xffff0000, v33
	v_max_f32_e32 v176, 0xda24260, v84
	v_max_f32_e32 v177, 0xda24260, v85
	v_rcp_f32_e32 v176, v176
	v_rcp_f32_e32 v177, v177
	v_pk_mul_f32 v[244:245], v[84:85], v[244:245]
	v_pk_mul_f32 v[174:175], v[176:177], v[174:175]
	v_cvt_pk_bf16_f32 v244, v244, v245
	v_cvt_pk_bf16_f32 v174, v174, v175
	ds_write_b32 v253, v174
	ds_write_b32 v86, v244
	global_load_dwordx4 v[14:17], v241, s[100:101]
	v_add_u32_e32 v176, v137, v73
	v_add_u32_e32 v147, v137, v71
	s_waitcnt lgkmcnt(0)
	s_barrier
	ds_read_b128 v[246:249], v136
	ds_read_b128 v[172:175], v147
	ds_read_b128 v[198:201], v147 offset:4352
	ds_read_b128 v[202:205], v147 offset:8704
	s_waitcnt lgkmcnt(2)
	v_mfma_f32_16x16x32_bf16 v[88:91], v[246:249], v[172:175], 0
	ds_read_b128 v[172:175], v176
	s_waitcnt lgkmcnt(2)
	v_mfma_f32_16x16x32_bf16 v[92:95], v[246:249], v[198:201], 0
	ds_read_b128 v[250:253], v136 offset:64
	ds_read_b128 v[198:201], v147 offset:64
	s_waitcnt lgkmcnt(3)
	v_mfma_f32_16x16x32_bf16 v[168:171], v[246:249], v[202:205], 0
	ds_read_b128 v[202:205], v147 offset:4416
	s_waitcnt lgkmcnt(3)
	v_mfma_f32_16x16x32_bf16 v[84:87], v[246:249], v[172:175], 0
	ds_read_b128 v[172:175], v147 offset:8768
	s_waitcnt lgkmcnt(2)
	v_mfma_f32_16x16x32_bf16 v[88:91], v[250:253], v[198:201], v[88:91]
	ds_read_b128 v[198:201], v176 offset:64
	global_load_dwordx4 v[26:29], v242, s[100:101]
	s_waitcnt lgkmcnt(2)
	v_mfma_f32_16x16x32_bf16 v[92:95], v[250:253], v[202:205], v[92:95]
	ds_read_b128 v[246:249], v136 offset:128
	ds_read_b128 v[202:205], v147 offset:128
	s_waitcnt lgkmcnt(3)
	v_mfma_f32_16x16x32_bf16 v[168:171], v[250:253], v[172:175], v[168:171]
	ds_read_b128 v[172:175], v147 offset:4480
	s_waitcnt lgkmcnt(3)
	v_mfma_f32_16x16x32_bf16 v[84:87], v[250:253], v[198:201], v[84:87]
	ds_read_b128 v[198:201], v147 offset:8832
	s_waitcnt lgkmcnt(2)
	v_mfma_f32_16x16x32_bf16 v[88:91], v[246:249], v[202:205], v[88:91]
	ds_read_b128 v[202:205], v176 offset:128
	s_waitcnt lgkmcnt(2)
	v_mfma_f32_16x16x32_bf16 v[92:95], v[246:249], v[172:175], v[92:95]
	ds_read_b128 v[250:253], v136 offset:192
	ds_read_b128 v[172:175], v147 offset:192
	s_waitcnt lgkmcnt(3)
	v_mfma_f32_16x16x32_bf16 v[168:171], v[246:249], v[198:201], v[168:171]
	ds_read_b128 v[198:201], v147 offset:4544
	s_waitcnt lgkmcnt(3)
	v_mfma_f32_16x16x32_bf16 v[84:87], v[246:249], v[202:205], v[84:87]
	ds_read_b128 v[202:205], v147 offset:8896
	s_waitcnt lgkmcnt(2)
	v_mfma_f32_16x16x32_bf16 v[88:91], v[250:253], v[172:175], v[88:91]
	ds_read_b128 v[172:175], v176 offset:192
	s_waitcnt lgkmcnt(2)
	v_mfma_f32_16x16x32_bf16 v[92:95], v[250:253], v[198:201], v[92:95]
	s_waitcnt lgkmcnt(1)
	v_mfma_f32_16x16x32_bf16 v[168:171], v[250:253], v[202:205], v[168:171]
	s_waitcnt lgkmcnt(0)
	v_mfma_f32_16x16x32_bf16 v[84:87], v[250:253], v[172:175], v[84:87]
	s_nop 7
	v_cvt_pk_bf16_f32 v88, v88, s0
	v_cvt_pk_bf16_f32 v89, v89, s0
	v_cvt_pk_bf16_f32 v90, v90, s0
	v_cvt_pk_bf16_f32 v91, v91, s0
	v_cndmask_b32_e64 v88, 0, v88, s[42:43]
	v_cndmask_b32_e64 v89, 0, v89, s[44:45]
	v_cndmask_b32_e64 v90, 0, v90, s[46:47]
	v_cndmask_b32_e64 v91, 0, v91, s[48:49]
	v_perm_b32 v88, v89, v88, s21
	v_perm_b32 v89, v91, v90, s21
	v_add_u32_e32 v90, v138, v75
	global_load_dwordx4 v[30:33], v243, s[100:101]
	ds_write_b64 v90, v[88:89]
	v_cvt_pk_bf16_f32 v88, v92, s0
	v_cvt_pk_bf16_f32 v89, v93, s0
	v_cvt_pk_bf16_f32 v91, v94, s0
	v_cvt_pk_bf16_f32 v92, v95, s0
	v_cndmask_b32_e64 v88, 0, v88, s[50:51]
	v_cndmask_b32_e64 v89, 0, v89, s[52:53]
	v_cndmask_b32_e64 v91, 0, v91, s[54:55]
	v_cndmask_b32_e64 v92, 0, v92, s[56:57]
	v_perm_b32 v88, v89, v88, s21
	v_perm_b32 v89, v92, v91, s21
	ds_write_b64 v90, v[88:89] offset:2304
	v_cvt_pk_bf16_f32 v88, v168, s0
	v_cvt_pk_bf16_f32 v89, v169, s0
	v_cvt_pk_bf16_f32 v91, v170, s0
	v_cvt_pk_bf16_f32 v92, v171, s0
	v_cvt_pk_bf16_f32 v84, v84, s0
	v_cvt_pk_bf16_f32 v85, v85, s0
	v_cvt_pk_bf16_f32 v86, v86, s0
	v_cvt_pk_bf16_f32 v87, v87, s0
	v_cndmask_b32_e64 v88, 0, v88, s[58:59]
	v_cndmask_b32_e64 v89, 0, v89, s[60:61]
	v_cndmask_b32_e64 v91, 0, v91, s[62:63]
	v_cndmask_b32_e64 v92, 0, v92, s[64:65]
	v_cndmask_b32_e64 v84, 0, v84, s[66:67]
	v_cndmask_b32_e64 v85, 0, v85, s[68:69]
	v_cndmask_b32_e64 v86, 0, v86, s[70:71]
	v_cndmask_b32_e64 v87, 0, v87, s[72:73]
	v_perm_b32 v88, v89, v88, s21
	v_perm_b32 v89, v92, v91, s21
	v_perm_b32 v84, v85, v84, s21
	v_perm_b32 v85, v87, v86, s21
	v_add_u32_e32 v86, v138, v96
	ds_write_b64 v90, v[88:89] offset:4608
	ds_write_b64 v86, v[84:85]
	s_waitcnt lgkmcnt(0)
	s_barrier
	ds_read_b64_tr_b16 v[84:85], v164
	ds_read_b64_tr_b16 v[86:87], v164 offset:1088
	ds_read_b128 v[88:91], v139
	ds_read_b128 v[92:95], v140
	s_waitcnt lgkmcnt(1)
	v_mfma_f32_16x16x32_bf16 v[88:91], v[88:91], v[84:87], 0
	v_add_u32_e32 v147, v106, v71
	v_add_u32_e32 v176, v106, v73
	s_waitcnt lgkmcnt(0)
	v_mfma_f32_16x16x32_bf16 v[88:91], v[92:95], v[84:87], v[88:91]
	ds_read_b128 v[92:95], v141
	ds_read_b128 v[168:171], v142
	s_waitcnt lgkmcnt(1)
	v_mfma_f32_16x16x32_bf16 v[92:95], v[92:95], v[84:87], 0
	s_waitcnt lgkmcnt(0)
	v_mfma_f32_16x16x32_bf16 v[92:95], v[168:171], v[84:87], v[92:95]
	ds_read_b128 v[168:171], v143
	ds_read_b128 v[172:175], v144
	s_waitcnt lgkmcnt(1)
	v_mfma_f32_16x16x32_bf16 v[168:171], v[168:171], v[84:87], 0
	s_waitcnt lgkmcnt(0)
	v_mfma_f32_16x16x32_bf16 v[168:171], v[172:175], v[84:87], v[168:171]
	ds_read_b128 v[172:175], v145
	ds_read_b128 v[198:201], v152
	s_waitcnt lgkmcnt(1)
	v_mfma_f32_16x16x32_bf16 v[172:175], v[172:175], v[84:87], 0
	s_waitcnt lgkmcnt(0)
	v_mfma_f32_16x16x32_bf16 v[84:87], v[198:201], v[84:87], v[172:175]
	s_nop 5
	ds_read_b64_tr_b16 v[172:173], v165
	ds_read_b64_tr_b16 v[174:175], v165 offset:1088
	ds_read_b128 v[198:201], v153
	ds_read_b128 v[202:205], v154
	s_waitcnt lgkmcnt(1)
	v_mfma_f32_16x16x32_bf16 v[88:91], v[198:201], v[172:175], v[88:91]
	s_waitcnt lgkmcnt(0)
	v_mfma_f32_16x16x32_bf16 v[88:91], v[202:205], v[172:175], v[88:91]
	ds_read_b128 v[198:201], v155
	ds_read_b128 v[202:205], v156
	s_waitcnt lgkmcnt(1)
	v_mfma_f32_16x16x32_bf16 v[92:95], v[198:201], v[172:175], v[92:95]
	s_waitcnt lgkmcnt(0)
	v_mfma_f32_16x16x32_bf16 v[92:95], v[202:205], v[172:175], v[92:95]
	ds_read_b128 v[198:201], v157
	ds_read_b128 v[202:205], v158
	s_waitcnt lgkmcnt(1)
	v_mfma_f32_16x16x32_bf16 v[168:171], v[198:201], v[172:175], v[168:171]
	s_waitcnt lgkmcnt(0)
	v_mfma_f32_16x16x32_bf16 v[168:171], v[202:205], v[172:175], v[168:171]
	ds_read_b128 v[198:201], v159
	ds_read_b128 v[202:205], v160
	s_waitcnt lgkmcnt(1)
	v_mfma_f32_16x16x32_bf16 v[84:87], v[198:201], v[172:175], v[84:87]
	s_waitcnt lgkmcnt(0)
	v_mfma_f32_16x16x32_bf16 v[84:87], v[202:205], v[172:175], v[84:87]
	ds_read_b128 v[172:175], v147
	ds_read_b128 v[198:201], v147 offset:4352
	ds_read_b128 v[202:205], v147 offset:8704
	ds_read_b128 v[246:249], v176
	s_lshl_b32 s80, s14, 8
	ds_read_b128 v[250:253], v147 offset:64
	s_waitcnt vmcnt(15) lgkmcnt(4)
	v_mfma_f32_16x16x32_bf16 v[88:91], v[172:175], v[62:65], v[88:91]
	ds_read_b128 v[172:175], v147 offset:4416
	s_waitcnt lgkmcnt(4)
	v_mfma_f32_16x16x32_bf16 v[92:95], v[198:201], v[62:65], v[92:95]
	ds_read_b128 v[198:201], v147 offset:8768
	s_waitcnt lgkmcnt(4)
	v_mfma_f32_16x16x32_bf16 v[168:171], v[202:205], v[62:65], v[168:171]
	ds_read_b128 v[202:205], v176 offset:64
	s_waitcnt lgkmcnt(4)
	v_mfma_f32_16x16x32_bf16 v[84:87], v[246:249], v[62:65], v[84:87]
	ds_read_b128 v[246:249], v147 offset:128
	s_waitcnt vmcnt(14) lgkmcnt(4)
	v_mfma_f32_16x16x32_bf16 v[88:91], v[250:253], v[58:61], v[88:91]
	ds_read_b128 v[250:253], v147 offset:4480
	s_waitcnt lgkmcnt(4)
	v_mfma_f32_16x16x32_bf16 v[92:95], v[172:175], v[58:61], v[92:95]
	ds_read_b128 v[172:175], v147 offset:8832
	s_waitcnt lgkmcnt(4)
	v_mfma_f32_16x16x32_bf16 v[168:171], v[198:201], v[58:61], v[168:171]
	ds_read_b128 v[198:201], v176 offset:128
	s_waitcnt lgkmcnt(4)
	v_mfma_f32_16x16x32_bf16 v[84:87], v[202:205], v[58:61], v[84:87]
	ds_read_b128 v[202:205], v147 offset:192
	s_waitcnt vmcnt(13) lgkmcnt(4)
	v_mfma_f32_16x16x32_bf16 v[88:91], v[246:249], v[54:57], v[88:91]
	ds_read_b128 v[246:249], v147 offset:4544
	s_waitcnt lgkmcnt(4)
	v_mfma_f32_16x16x32_bf16 v[92:95], v[250:253], v[54:57], v[92:95]
	ds_read_b128 v[250:253], v147 offset:8896
	s_waitcnt lgkmcnt(4)
	v_mfma_f32_16x16x32_bf16 v[168:171], v[172:175], v[54:57], v[168:171]
	ds_read_b128 v[172:175], v176 offset:192
	s_waitcnt lgkmcnt(4)
	v_mfma_f32_16x16x32_bf16 v[84:87], v[198:201], v[54:57], v[84:87]
	ds_read_b128 v[198:201], v147 offset:17408
	s_waitcnt vmcnt(12) lgkmcnt(4)
	v_mfma_f32_16x16x32_bf16 v[88:91], v[202:205], v[50:53], v[88:91]
	ds_read_b128 v[202:205], v147 offset:21760
	s_waitcnt lgkmcnt(4)
	v_mfma_f32_16x16x32_bf16 v[92:95], v[246:249], v[50:53], v[92:95]
	ds_read_b128 v[246:249], v147 offset:26112
	s_waitcnt lgkmcnt(4)
	v_mfma_f32_16x16x32_bf16 v[168:171], v[250:253], v[50:53], v[168:171]
	ds_read_b128 v[250:253], v176 offset:17408
	s_waitcnt lgkmcnt(4)
	v_mfma_f32_16x16x32_bf16 v[84:87], v[172:175], v[50:53], v[84:87]
	ds_read_b128 v[172:175], v147 offset:17472
	s_waitcnt vmcnt(11) lgkmcnt(4)
	v_mfma_f32_16x16x32_bf16 v[88:91], v[198:201], v[46:49], v[88:91]
	ds_read_b128 v[198:201], v147 offset:21824
	s_waitcnt lgkmcnt(4)
	v_mfma_f32_16x16x32_bf16 v[92:95], v[202:205], v[46:49], v[92:95]
	ds_read_b128 v[202:205], v147 offset:26176
	s_waitcnt lgkmcnt(4)
	v_mfma_f32_16x16x32_bf16 v[168:171], v[246:249], v[46:49], v[168:171]
	ds_read_b128 v[246:249], v176 offset:17472
	s_waitcnt lgkmcnt(4)
	v_mfma_f32_16x16x32_bf16 v[84:87], v[250:253], v[46:49], v[84:87]
	ds_read_b128 v[250:253], v147 offset:17536
	s_waitcnt vmcnt(10) lgkmcnt(4)
	v_mfma_f32_16x16x32_bf16 v[88:91], v[172:175], v[42:45], v[88:91]
	ds_read_b128 v[172:175], v147 offset:21888
	s_waitcnt lgkmcnt(4)
	v_mfma_f32_16x16x32_bf16 v[92:95], v[198:201], v[42:45], v[92:95]
	ds_read_b128 v[198:201], v147 offset:26240
	s_waitcnt lgkmcnt(4)
	v_mfma_f32_16x16x32_bf16 v[168:171], v[202:205], v[42:45], v[168:171]
	ds_read_b128 v[202:205], v176 offset:17536
	s_waitcnt lgkmcnt(4)
	v_mfma_f32_16x16x32_bf16 v[84:87], v[246:249], v[42:45], v[84:87]
	ds_read_b128 v[246:249], v147 offset:17600
	s_waitcnt vmcnt(9) lgkmcnt(4)
	v_mfma_f32_16x16x32_bf16 v[88:91], v[250:253], v[38:41], v[88:91]
	ds_read_b128 v[250:253], v147 offset:21952
	s_waitcnt lgkmcnt(4)
	v_mfma_f32_16x16x32_bf16 v[92:95], v[172:175], v[38:41], v[92:95]
	ds_read_b128 v[172:175], v147 offset:26304
	s_waitcnt lgkmcnt(4)
	v_mfma_f32_16x16x32_bf16 v[168:171], v[198:201], v[38:41], v[168:171]
	ds_read_b128 v[198:201], v176 offset:17600
	s_waitcnt lgkmcnt(4)
	v_mfma_f32_16x16x32_bf16 v[84:87], v[202:205], v[38:41], v[84:87]
	v_lshl_add_u64 v[58:59], vcc, 0, v[76:77]
	s_waitcnt vmcnt(8) lgkmcnt(3)
	v_mfma_f32_16x16x32_bf16 v[42:45], v[246:249], v[34:37], v[88:91]
	s_waitcnt lgkmcnt(2)
	v_mfma_f32_16x16x32_bf16 v[46:49], v[250:253], v[34:37], v[92:95]
	s_waitcnt lgkmcnt(1)
	v_mfma_f32_16x16x32_bf16 v[50:53], v[172:175], v[34:37], v[168:171]
	s_waitcnt lgkmcnt(0)
	v_mfma_f32_16x16x32_bf16 v[38:41], v[198:201], v[34:37], v[84:87]
	v_lshlrev_b64 v[34:35], 8, v[58:59]
	v_lshl_add_u64 v[34:35], s[16:17], 0, v[34:35]
	v_lshl_add_u64 v[34:35], v[34:35], 0, v[0:1]
	s_mov_b64 s[16:17], 0x10000000
	v_lshl_add_u64 v[36:37], v[34:35], 0, s[16:17]
	v_add_co_u32_e32 v34, vcc, s15, v34
	v_lshlrev_b64 v[58:59], 11, v[58:59]
	s_nop 0
	v_addc_co_u32_e32 v35, vcc, 0, v35, vcc
	global_load_dwordx4 v[54:57], v[34:35], off
	s_nop 0
	global_load_dwordx4 v[34:37], v[36:37], off offset:16
	s_barrier
	ds_write2_b32 v166, v42, v43 offset1:132
	v_add_u32_e32 v42, 0x400, v166
	ds_write2_b32 v42, v44, v45 offset0:8 offset1:140
	v_add_u32_e32 v42, 0x2000, v166
	ds_write2_b32 v42, v46, v47 offset0:64 offset1:196
	v_add_u32_e32 v42, 0x2400, v166
	ds_write2_b32 v42, v48, v49 offset0:72 offset1:204
	v_add_u32_e32 v42, 0x4200, v166
	ds_write2_b32 v42, v50, v51 offset1:132
	v_add_u32_e32 v42, 0x4600, v166
	ds_write2_b32 v42, v52, v53 offset0:8 offset1:140
	v_add_u32_e32 v42, 0x6200, v166
	ds_write2_b32 v42, v38, v39 offset0:64 offset1:196
	v_add_u32_e32 v38, 0x6600, v166
	ds_write2_b32 v38, v40, v41 offset0:72 offset1:204
	s_waitcnt lgkmcnt(0)
	s_barrier
	ds_read_b128 v[50:53], v162
	ds_read_b128 v[46:49], v162 offset:16
	ds_read_b128 v[42:45], v162 offset:32
	ds_read_b128 v[38:41], v162 offset:48
	v_lshl_add_u64 v[58:59], s[74:75], 0, v[58:59]
	s_waitcnt lgkmcnt(3)
	v_pk_mul_f32 v[60:61], v[52:53], v[52:53]
	v_pk_mul_f32 v[62:63], v[50:51], v[50:51]
	v_lshl_add_u64 v[58:59], v[58:59], 0, s[80:81]
	v_pk_mov_b32 v[64:65], v[62:63], v[60:61] op_sel:[1,0]
	v_mov_b32_e32 v63, v61
	v_pk_add_f32 v[60:61], v[64:65], v[62:63]
	s_waitcnt lgkmcnt(2)
	v_pk_mul_f32 v[62:63], v[48:49], v[48:49]
	v_pk_mul_f32 v[64:65], v[46:47], v[46:47]
	v_pk_add_f32 v[60:61], v[60:61], v[60:61] op_sel:[0,1] op_sel_hi:[1,0]
	v_pk_mov_b32 v[84:85], v[64:65], v[62:63] op_sel:[1,0]
	v_mov_b32_e32 v65, v63
	v_pk_add_f32 v[62:63], v[84:85], v[64:65]
	s_waitcnt lgkmcnt(0)
	v_mul_f32_e32 v64, v38, v38
	v_mul_f32_e32 v65, v39, v39
	v_pk_add_f32 v[62:63], v[62:63], v[62:63] op_sel:[0,1] op_sel_hi:[1,0]
	v_mov_b32_e32 v61, v64
	v_mov_b32_e32 v63, v65
	v_pk_add_f32 v[60:61], v[60:61], v[62:63]
	v_mul_f32_e32 v62, v43, v43
	v_mul_f32_e32 v64, v45, v45
	v_mul_f32_e32 v84, v40, v40
	v_mul_f32_e32 v85, v41, v41
	v_pk_fma_f32 v[62:63], v[42:43], v[42:43], v[62:63] op_sel_hi:[1,1,0]
	v_pk_fma_f32 v[64:65], v[44:45], v[44:45], v[64:65] op_sel_hi:[1,1,0]
	v_mov_b32_e32 v63, v84
	v_mov_b32_e32 v65, v85
	v_pk_add_f32 v[62:63], v[62:63], v[64:65]
	v_lshl_add_u64 v[86:87], v[58:59], 0, v[0:1]
	v_pk_add_f32 v[60:61], v[60:61], v[62:63]
	s_waitcnt vmcnt(1)
	v_lshlrev_b32_e32 v92, 16, v54
	v_add_f32_e32 v60, v60, v61
	ds_bpermute_b32 v61, v97, v60
	v_and_b32_e32 v93, 0xffff0000, v54
	v_lshlrev_b32_e32 v94, 16, v55
	v_and_b32_e32 v95, 0xffff0000, v55
	v_lshlrev_b32_e32 v88, 16, v56
	s_waitcnt lgkmcnt(0)
	v_add_f32_e32 v60, v60, v61
	ds_bpermute_b32 v61, v98, v60
	v_and_b32_e32 v89, 0xffff0000, v56
	v_lshlrev_b32_e32 v90, 16, v57
	v_and_b32_e32 v91, 0xffff0000, v57
	s_waitcnt lgkmcnt(0)
	v_add_f32_e32 v60, v60, v61
	ds_bpermute_b32 v61, v163, v60
	s_waitcnt lgkmcnt(0)
	v_add_f32_e32 v60, v60, v61
	v_fmamk_f32 v60, v60, 0x3c000000, v178
	v_cmp_gt_f32_e32 vcc, s22, v60
	v_mul_f32_e32 v61, 0x4b800000, v60
	s_nop 0
	v_cndmask_b32_e32 v60, v60, v61, vcc
	v_rsq_f32_e32 v60, v60
	s_nop 0
	v_mul_f32_e32 v61, 0x45800000, v60
	v_cndmask_b32_e32 v84, v60, v61, vcc
	v_pk_mul_f32 v[52:53], v[52:53], v[84:85] op_sel_hi:[1,0]
	v_pk_mul_f32 v[50:51], v[50:51], v[84:85] op_sel_hi:[1,0]
	v_pk_mul_f32 v[48:49], v[48:49], v[84:85] op_sel_hi:[1,0]
	v_pk_mul_f32 v[46:47], v[46:47], v[84:85] op_sel_hi:[1,0]
	v_pk_mul_f32 v[44:45], v[44:45], v[84:85] op_sel_hi:[1,0]
	v_pk_mul_f32 v[42:43], v[42:43], v[84:85] op_sel_hi:[1,0]
	v_pk_mul_f32 v[40:41], v[40:41], v[84:85] op_sel_hi:[1,0]
	v_pk_mul_f32 v[38:39], v[38:39], v[84:85] op_sel_hi:[1,0]
	s_and_b64 vcc, exec, s[12:13]
	v_pk_mul_f32 v[38:39], v[232:233], v[38:39]
	v_pk_mul_f32 v[42:43], v[228:229], v[42:43]
	v_pk_mul_f32 v[46:47], v[224:225], v[46:47]
	v_pk_mul_f32 v[50:51], v[220:221], v[50:51]
	v_pk_mul_f32 v[52:53], v[222:223], v[52:53]
	v_pk_mul_f32 v[48:49], v[226:227], v[48:49]
	v_pk_mul_f32 v[52:53], v[52:53], v[94:95]
	v_pk_mul_f32 v[50:51], v[50:51], v[92:93]
	v_pk_mul_f32 v[62:63], v[48:49], v[90:91]
	v_pk_mul_f32 v[48:49], v[46:47], v[88:89]
	v_cvt_pk_bf16_f32 v46, v50, v51
	v_cvt_pk_bf16_f32 v47, v52, v53
	v_cvt_pk_bf16_f32 v48, v48, v49
	v_cvt_pk_bf16_f32 v49, v62, v63
	global_store_dwordx4 v[86:87], v[46:49], off offset:1024
	v_pk_mul_f32 v[44:45], v[230:231], v[44:45]
	v_pk_mul_f32 v[40:41], v[234:235], v[40:41]
	s_waitcnt vmcnt(1)
	v_lshlrev_b32_e32 v46, 16, v34
	v_and_b32_e32 v47, 0xffff0000, v34
	v_lshlrev_b32_e32 v34, 16, v35
	v_and_b32_e32 v35, 0xffff0000, v35
	v_lshlrev_b32_e32 v48, 16, v36
	v_and_b32_e32 v49, 0xffff0000, v36
	v_lshlrev_b32_e32 v36, 16, v37
	v_and_b32_e32 v37, 0xffff0000, v37
	v_pk_mul_f32 v[44:45], v[44:45], v[34:35]
	v_pk_mul_f32 v[34:35], v[42:43], v[46:47]
	v_pk_mul_f32 v[40:41], v[40:41], v[36:37]
	v_pk_mul_f32 v[36:37], v[38:39], v[48:49]
	v_cvt_pk_bf16_f32 v34, v34, v35
	v_cvt_pk_bf16_f32 v35, v44, v45
	v_cvt_pk_bf16_f32 v36, v36, v37
	v_cvt_pk_bf16_f32 v37, v40, v41
	global_store_dwordx4 v[86:87], v[34:37], off offset:1040
	s_barrier
	s_cbranch_vccnz .LBB0_455
